# adds hand-scheduled fast tile body for the selected stream (far block, one query group active, no rescale): V reads under the softmax, state accumulated in place; falls through to the original body ot
# speedup vs baseline: 1.0222x; 1.0182x over previous
; DEV void qk64(const LAS unsigned char* Kb, const AttnCtx& C, const ab8 (&qf)[2][2], f32x4 (&s)[2][4], float init0, float init1, bool a0, bool a1) {
;     ab8 k0[4], k1[4];
; #pragma unroll
;     for (int kt = 0; kt < 4; ++kt) { k0[kt] = *(const LAS ab8*)(Kb + swz(16 * kt + C.n, C.q4)); k1[kt] = *(const LAS ab8*)(Kb + swz(16 * kt + C.n, 4 + C.q4)); }
;     __builtin_amdgcn_sched_barrier(0);
; #pragma unroll
;     for (int kt = 0; kt < 4; ++kt) {
;         if (a0) { f32x4 c = {init0, init0, init0, init0}; c = __builtin_amdgcn_mfma_f32_16x16x32_bf16(k0[kt], qf[0][0], c, 0, 0, 0); s[0][kt] = __builtin_amdgcn_mfma_f32_16x16x32_bf16(k1[kt], qf[0][1], c, 0, 0, 0); }
;         if (a1) { f32x4 c = {init1, init1, init1, init1}; c = __builtin_amdgcn_mfma_f32_16x16x32_bf16(k0[kt], qf[1][0], c, 0, 0, 0); s[1][kt] = __builtin_amdgcn_mfma_f32_16x16x32_bf16(k1[kt], qf[1][1], c, 0, 0, 0); }
; DEV void ref_step(f32x4 (&s)[4], float& m, f32x4 (&O)[4], f32x4& L, ab8 (&pf)[2], bool colact) {
;     ...
;     const bool slow = (colact && m == NEG_INF) || mx > 64.f;
;     if (__any(slow)) {
;         mx = fmaxf(mx, __shfl_xor(mx, 16)); mx = fmaxf(mx, __shfl_xor(mx, 32));
;         const bool un = (m == NEG_INF);
;         const float d = (mx == NEG_INF) ? 0.f : (un ? mx : fmaxf(mx, 0.f));
;         const float sc = un ? 1.f : __builtin_amdgcn_exp2f(-d);
; #pragma unroll
;         for (int kt = 0; kt < 4; ++kt) s[kt] = s[kt] - d;
; #pragma unroll
;         for (int dt = 0; dt < 4; ++dt) O[dt] = O[dt] * sc;
;         L = L * sc;
;         m = un ? ((mx == NEG_INF) ? NEG_INF : mx) : m + d;
;     }
; #pragma unroll
;     for (int kt = 0; kt < 4; ++kt)
; #pragma unroll
;         for (int i = 0; i < 4; ++i) s[kt][i] = __builtin_amdgcn_exp2f(s[kt][i]);
; #pragma unroll
;     for (int j = 0; j < 2; ++j) { v4u w; w.x = cvtpk(s[2 * j][0], s[2 * j][1]); w.y = cvtpk(s[2 * j][2], s[2 * j][3]); w.z = cvtpk(s[2 * j + 1][0], s[2 * j + 1][1]); w.w = cvtpk(s[2 * j + 1][2], s[2 * j + 1][3]); pf[j] = __builtin_bit_cast(ab8, w); }
; }
; template <bool PV, bool WITHL>
; DEV void pv64(const LAS unsigned char* Vb, const AttnCtx& C, const ab8 (&pf)[2][2], f32x4 (&O)[2][4], f32x4 (&L)[2], bool a0, bool a1) {
;     if (PV) {
;         const int vr = 4 * C.q4 + (C.n >> 2), vc = (C.n & 3) >> 1, vs = 8 * (C.n & 1);
;         ab8 vf[4][2];
; #pragma unroll
;         for (int dt = 0; dt < 4; ++dt)
; #pragma unroll
.Lmy_sel_pd:
	s_mul_i32 s8, s8, 0xc000
	s_add_i32 s9, s28, -2
	s_add_i32 s27, s8, 0
	s_cmp_ge_i32 s9, s23
	s_cbranch_scc1 .LBB0_1196
	s_waitcnt lgkmcnt(0)
	s_and_b32 s29, s98, 0xffff
	s_lshr_b32 s8, s98, 16
	s_and_b32 s9, s8, 0xff
	s_cmp_eq_u32 s9, 0
	s_cbranch_scc1 .LBB0_1196
	s_cmp_ge_i32 s29, s22
	s_cbranch_scc1 .Lmy_orig_0
	s_and_b32 s9, s8, 15
	s_and_b32 s10, s8, 0xf0
	s_cmp_lg_u32 s9, 0
	s_cselect_b32 s11, 1, 0
	s_cmp_lg_u32 s10, 0
	s_cselect_b32 s12, 1, 0
	s_add_i32 s13, s11, s12
	s_cmp_eq_u32 s13, 2
	s_cbranch_scc1 .Lmy_orig_0
	s_cmp_eq_u32 s11, 1
	s_cbranch_scc0 .Lmy_f1_0
	v_add3_u32 v228, s27, v199, v198
	v_add3_u32 v229, s27, v197, v198
	ds_read_b128 v[66:69], v228 offset:0
	ds_read_b128 v[70:73], v229 offset:0
	ds_read_b128 v[74:77], v228 offset:2048
	ds_read_b128 v[78:81], v229 offset:2048
	ds_read_b128 v[82:85], v228 offset:4096
	ds_read_b128 v[86:89], v229 offset:4096
	ds_read_b128 v[90:93], v228 offset:6144
	ds_read_b128 v[94:97], v229 offset:6144
	v_and_b32_e32 v239, s8, v206
	v_cmp_ne_u32_e64 s[10:11], 0, v239
	v_cmp_eq_f32_e64 s[12:13], s3, v213
	v_add_u32_e32 v234, s27, v200
	v_add3_u32 v235, v234, v201, v209
	v_add3_u32 v236, v234, v202, v209
	v_cndmask_b32_e64 v230, v213, 0, s[12:13]
	v_sub_f32_e32 v230, v175, v230
	v_add3_u32 v237, v234, v203, v209
	v_add3_u32 v238, v234, v204, v209
	v_cndmask_b32_e64 v230, v173, v230, s[10:11]
	s_and_b64 s[12:13], s[10:11], s[12:13]
	v_mov_b32_e32 v231, v230
	v_mov_b32_e32 v232, v230
	v_mov_b32_e32 v233, v230
	s_waitcnt lgkmcnt(0)
	v_mfma_f32_16x16x32_bf16 v[66:69], v[66:69], v[2:5], v[230:233]
	v_mfma_f32_16x16x32_bf16 v[74:77], v[74:77], v[2:5], v[230:233]
	v_mfma_f32_16x16x32_bf16 v[82:85], v[82:85], v[2:5], v[230:233]
	v_mfma_f32_16x16x32_bf16 v[90:93], v[90:93], v[2:5], v[230:233]
	v_mfma_f32_16x16x32_bf16 v[66:69], v[70:73], v[6:9], v[66:69]
	v_mfma_f32_16x16x32_bf16 v[74:77], v[78:81], v[6:9], v[74:77]
	v_mfma_f32_16x16x32_bf16 v[82:85], v[86:89], v[6:9], v[82:85]
	v_mfma_f32_16x16x32_bf16 v[90:93], v[94:97], v[6:9], v[90:93]
	ds_read_b64_tr_b16 v[98:99], v235 offset:8192
	ds_read_b64_tr_b16 v[100:101], v235 offset:10240
	ds_read_b64_tr_b16 v[102:103], v235 offset:12288
	ds_read_b64_tr_b16 v[104:105], v235 offset:14336
	ds_read_b64_tr_b16 v[106:107], v236 offset:8192
	ds_read_b64_tr_b16 v[108:109], v236 offset:10240
	ds_read_b64_tr_b16 v[110:111], v236 offset:12288
	ds_read_b64_tr_b16 v[112:113], v236 offset:14336
	ds_read_b64_tr_b16 v[114:115], v237 offset:8192
	ds_read_b64_tr_b16 v[116:117], v237 offset:10240
	ds_read_b64_tr_b16 v[118:119], v237 offset:12288
	ds_read_b64_tr_b16 v[120:121], v237 offset:14336
	ds_read_b64_tr_b16 v[122:123], v238 offset:8192
	ds_read_b64_tr_b16 v[124:125], v238 offset:10240
	ds_read_b64_tr_b16 v[126:127], v238 offset:12288
	ds_read_b64_tr_b16 v[128:129], v238 offset:14336
	v_max3_f32 v239, v66, v67, v68
	v_max3_f32 v240, v69, v74, v75
	v_max3_f32 v241, v76, v77, v82
	v_max3_f32 v242, v83, v84, v85
	v_max3_f32 v239, v239, v240, v90
	v_max3_f32 v241, v241, v242, v91
	v_max3_f32 v239, v239, v92, v93
	v_max_f32_e32 v239, v239, v241
	v_cmp_lt_f32_e32 vcc, s96, v239
	s_or_b64 s[12:13], s[12:13], vcc
	s_cmp_lg_u64 s[12:13], 0
	s_cbranch_scc1 .Lmy_slow_0_0
	v_exp_f32_e32 v66, v66
	v_exp_f32_e32 v67, v67
	v_exp_f32_e32 v68, v68
	v_exp_f32_e32 v69, v69
	v_exp_f32_e32 v74, v74
	v_exp_f32_e32 v75, v75
	v_exp_f32_e32 v76, v76
	v_exp_f32_e32 v77, v77
	v_exp_f32_e32 v82, v82
	v_exp_f32_e32 v83, v83
	v_exp_f32_e32 v84, v84
	v_exp_f32_e32 v85, v85
	v_exp_f32_e32 v90, v90
	v_exp_f32_e32 v91, v91
	v_exp_f32_e32 v92, v92
	v_exp_f32_e32 v93, v93
	v_cvt_pk_bf16_f32 v130, v66, v67
	v_cvt_pk_bf16_f32 v131, v68, v69
	v_cvt_pk_bf16_f32 v132, v74, v75
	v_cvt_pk_bf16_f32 v133, v76, v77
	v_cvt_pk_bf16_f32 v134, v82, v83
	v_cvt_pk_bf16_f32 v135, v84, v85
	v_cvt_pk_bf16_f32 v136, v90, v91
	v_cvt_pk_bf16_f32 v137, v92, v93
	s_nop 1
	s_waitcnt lgkmcnt(12)
	v_mfma_f32_16x16x32_bf16 v[62:65], v[98:101], v[130:133], v[62:65]
	v_mfma_f32_16x16x32_bf16 v[58:61], v[22:25], v[130:133], v[58:61]
	v_mfma_f32_16x16x32_bf16 v[62:65], v[102:105], v[134:137], v[62:65]
	s_waitcnt lgkmcnt(8)
	v_mfma_f32_16x16x32_bf16 v[54:57], v[106:109], v[130:133], v[54:57]
	v_mfma_f32_16x16x32_bf16 v[54:57], v[110:113], v[134:137], v[54:57]
	s_waitcnt lgkmcnt(4)
	v_mfma_f32_16x16x32_bf16 v[50:53], v[114:117], v[130:133], v[50:53]
	v_mfma_f32_16x16x32_bf16 v[58:61], v[22:25], v[134:137], v[58:61]
	v_mfma_f32_16x16x32_bf16 v[50:53], v[118:121], v[134:137], v[50:53]
	s_waitcnt lgkmcnt(0)
	v_mfma_f32_16x16x32_bf16 v[46:49], v[122:125], v[130:133], v[46:49]
	v_mfma_f32_16x16x32_bf16 v[46:49], v[126:129], v[134:137], v[46:49]
	s_nop 7
	s_branch .LBB0_1196
; DEV void qk64(const LAS unsigned char* Kb, const AttnCtx& C, const ab8 (&qf)[2][2], f32x4 (&s)[2][4], float init0, float init1, bool a0, bool a1) {
;     ab8 k0[4], k1[4];
; #pragma unroll
;     for (int kt = 0; kt < 4; ++kt) { k0[kt] = *(const LAS ab8*)(Kb + swz(16 * kt + C.n, C.q4)); k1[kt] = *(const LAS ab8*)(Kb + swz(16 * kt + C.n, 4 + C.q4)); }
;     __builtin_amdgcn_sched_barrier(0);
; #pragma unroll
;     for (int kt = 0; kt < 4; ++kt) {
;         if (a0) { f32x4 c = {init0, init0, init0, init0}; c = __builtin_amdgcn_mfma_f32_16x16x32_bf16(k0[kt], qf[0][0], c, 0, 0, 0); s[0][kt] = __builtin_amdgcn_mfma_f32_16x16x32_bf16(k1[kt], qf[0][1], c, 0, 0, 0); }
;         if (a1) { f32x4 c = {init1, init1, init1, init1}; c = __builtin_amdgcn_mfma_f32_16x16x32_bf16(k0[kt], qf[1][0], c, 0, 0, 0); s[1][kt] = __builtin_amdgcn_mfma_f32_16x16x32_bf16(k1[kt], qf[1][1], c, 0, 0, 0); }
; DEV void ref_step(f32x4 (&s)[4], float& m, f32x4 (&O)[4], f32x4& L, ab8 (&pf)[2], bool colact) {
;     ...
;     const bool slow = (colact && m == NEG_INF) || mx > 64.f;
;     if (__any(slow)) {
;         mx = fmaxf(mx, __shfl_xor(mx, 16)); mx = fmaxf(mx, __shfl_xor(mx, 32));
;         const bool un = (m == NEG_INF);
;         const float d = (mx == NEG_INF) ? 0.f : (un ? mx : fmaxf(mx, 0.f));
;         const float sc = un ? 1.f : __builtin_amdgcn_exp2f(-d);
; #pragma unroll
;         for (int kt = 0; kt < 4; ++kt) s[kt] = s[kt] - d;
; #pragma unroll
;         for (int dt = 0; dt < 4; ++dt) O[dt] = O[dt] * sc;
;         L = L * sc;
;         m = un ? ((mx == NEG_INF) ? NEG_INF : mx) : m + d;
;     }
; #pragma unroll
;     for (int kt = 0; kt < 4; ++kt)
; #pragma unroll
;         for (int i = 0; i < 4; ++i) s[kt][i] = __builtin_amdgcn_exp2f(s[kt][i]);
; #pragma unroll
;     for (int j = 0; j < 2; ++j) { v4u w; w.x = cvtpk(s[2 * j][0], s[2 * j][1]); w.y = cvtpk(s[2 * j][2], s[2 * j][3]); w.z = cvtpk(s[2 * j + 1][0], s[2 * j + 1][1]); w.w = cvtpk(s[2 * j + 1][2], s[2 * j + 1][3]); pf[j] = __builtin_bit_cast(ab8, w); }
; }
; template <bool PV, bool WITHL>
; DEV void pv64(const LAS unsigned char* Vb, const AttnCtx& C, const ab8 (&pf)[2][2], f32x4 (&O)[2][4], f32x4 (&L)[2], bool a0, bool a1) {
;     if (PV) {
;         const int vr = 4 * C.q4 + (C.n >> 2), vc = (C.n & 3) >> 1, vs = 8 * (C.n & 1);
;         ab8 vf[4][2];
; #pragma unroll
;         for (int dt = 0; dt < 4; ++dt)
; #pragma unroll
.Lmy_slow_0_0:
	s_waitcnt lgkmcnt(0)
	s_branch .Lmy_orig_0
.Lmy_f1_0:
	v_add3_u32 v228, s27, v199, v198
	v_add3_u32 v229, s27, v197, v198
	ds_read_b128 v[66:69], v228 offset:0
	ds_read_b128 v[70:73], v229 offset:0
	ds_read_b128 v[74:77], v228 offset:2048
	ds_read_b128 v[78:81], v229 offset:2048
	ds_read_b128 v[82:85], v228 offset:4096
	ds_read_b128 v[86:89], v229 offset:4096
	ds_read_b128 v[90:93], v228 offset:6144
	ds_read_b128 v[94:97], v229 offset:6144
	v_and_b32_e32 v239, s8, v207
	v_cmp_ne_u32_e64 s[10:11], 0, v239
	v_cmp_eq_f32_e64 s[12:13], s3, v212
	v_add_u32_e32 v234, s27, v200
	v_add3_u32 v235, v234, v201, v209
	v_add3_u32 v236, v234, v202, v209
	v_cndmask_b32_e64 v230, v212, 0, s[12:13]
	v_sub_f32_e32 v230, v175, v230
	v_add3_u32 v237, v234, v203, v209
	v_add3_u32 v238, v234, v204, v209
	v_cndmask_b32_e64 v230, v173, v230, s[10:11]
	s_and_b64 s[12:13], s[10:11], s[12:13]
	v_mov_b32_e32 v231, v230
	v_mov_b32_e32 v232, v230
	v_mov_b32_e32 v233, v230
	s_waitcnt lgkmcnt(0)
	v_mfma_f32_16x16x32_bf16 v[66:69], v[66:69], v[10:13], v[230:233]
	v_mfma_f32_16x16x32_bf16 v[74:77], v[74:77], v[10:13], v[230:233]
	v_mfma_f32_16x16x32_bf16 v[82:85], v[82:85], v[10:13], v[230:233]
	v_mfma_f32_16x16x32_bf16 v[90:93], v[90:93], v[10:13], v[230:233]
	v_mfma_f32_16x16x32_bf16 v[66:69], v[70:73], v[14:17], v[66:69]
	v_mfma_f32_16x16x32_bf16 v[74:77], v[78:81], v[14:17], v[74:77]
	v_mfma_f32_16x16x32_bf16 v[82:85], v[86:89], v[14:17], v[82:85]
	v_mfma_f32_16x16x32_bf16 v[90:93], v[94:97], v[14:17], v[90:93]
	ds_read_b64_tr_b16 v[98:99], v235 offset:8192
	ds_read_b64_tr_b16 v[100:101], v235 offset:10240
	ds_read_b64_tr_b16 v[102:103], v235 offset:12288
	ds_read_b64_tr_b16 v[104:105], v235 offset:14336
	ds_read_b64_tr_b16 v[106:107], v236 offset:8192
	ds_read_b64_tr_b16 v[108:109], v236 offset:10240
	ds_read_b64_tr_b16 v[110:111], v236 offset:12288
	ds_read_b64_tr_b16 v[112:113], v236 offset:14336
	ds_read_b64_tr_b16 v[114:115], v237 offset:8192
	ds_read_b64_tr_b16 v[116:117], v237 offset:10240
	ds_read_b64_tr_b16 v[118:119], v237 offset:12288
	ds_read_b64_tr_b16 v[120:121], v237 offset:14336
	ds_read_b64_tr_b16 v[122:123], v238 offset:8192
	ds_read_b64_tr_b16 v[124:125], v238 offset:10240
	ds_read_b64_tr_b16 v[126:127], v238 offset:12288
	ds_read_b64_tr_b16 v[128:129], v238 offset:14336
	v_max3_f32 v239, v66, v67, v68
	v_max3_f32 v240, v69, v74, v75
	v_max3_f32 v241, v76, v77, v82
	v_max3_f32 v242, v83, v84, v85
	v_max3_f32 v239, v239, v240, v90
	v_max3_f32 v241, v241, v242, v91
	v_max3_f32 v239, v239, v92, v93
	v_max_f32_e32 v239, v239, v241
	v_cmp_lt_f32_e32 vcc, s96, v239
	s_or_b64 s[12:13], s[12:13], vcc
	s_cmp_lg_u64 s[12:13], 0
	s_cbranch_scc1 .Lmy_slow_1_0
	v_exp_f32_e32 v66, v66
	v_exp_f32_e32 v67, v67
	v_exp_f32_e32 v68, v68
	v_exp_f32_e32 v69, v69
	v_exp_f32_e32 v74, v74
	v_exp_f32_e32 v75, v75
	v_exp_f32_e32 v76, v76
	v_exp_f32_e32 v77, v77
	v_exp_f32_e32 v82, v82
	v_exp_f32_e32 v83, v83
	v_exp_f32_e32 v84, v84
	v_exp_f32_e32 v85, v85
	v_exp_f32_e32 v90, v90
	v_exp_f32_e32 v91, v91
	v_exp_f32_e32 v92, v92
	v_exp_f32_e32 v93, v93
	v_cvt_pk_bf16_f32 v130, v66, v67
	v_cvt_pk_bf16_f32 v131, v68, v69
	v_cvt_pk_bf16_f32 v132, v74, v75
	v_cvt_pk_bf16_f32 v133, v76, v77
	v_cvt_pk_bf16_f32 v134, v82, v83
	v_cvt_pk_bf16_f32 v135, v84, v85
	v_cvt_pk_bf16_f32 v136, v90, v91
	v_cvt_pk_bf16_f32 v137, v92, v93
	s_nop 1
	s_waitcnt lgkmcnt(12)
	v_mfma_f32_16x16x32_bf16 v[38:41], v[98:101], v[130:133], v[38:41]
	v_mfma_f32_16x16x32_bf16 v[42:45], v[22:25], v[130:133], v[42:45]
	v_mfma_f32_16x16x32_bf16 v[38:41], v[102:105], v[134:137], v[38:41]
	s_waitcnt lgkmcnt(8)
	v_mfma_f32_16x16x32_bf16 v[34:37], v[106:109], v[130:133], v[34:37]
	v_mfma_f32_16x16x32_bf16 v[34:37], v[110:113], v[134:137], v[34:37]
	s_waitcnt lgkmcnt(4)
	v_mfma_f32_16x16x32_bf16 v[30:33], v[114:117], v[130:133], v[30:33]
	v_mfma_f32_16x16x32_bf16 v[42:45], v[22:25], v[134:137], v[42:45]
	v_mfma_f32_16x16x32_bf16 v[30:33], v[118:121], v[134:137], v[30:33]
	s_waitcnt lgkmcnt(0)
	v_mfma_f32_16x16x32_bf16 v[26:29], v[122:125], v[130:133], v[26:29]
	v_mfma_f32_16x16x32_bf16 v[26:29], v[126:129], v[134:137], v[26:29]
	s_nop 7
	s_branch .LBB0_1196

; #define NEG_INF (-__builtin_inff())
; template <bool LUTB, bool WINLO>
; DEV void mask_bias(f32x4 (&s)[4], const AttnCtx& C, int t, int p0, int pstep, bool colok) {
; #pragma unroll
;     for (int kt = 0; kt < 4; ++kt)
; #pragma unroll
;         for (int i = 0; i < 4; ++i) { const int rel = t - (p0 + pstep * (16 * kt + 4 * C.q4 + i));
;             bool ok = colok && rel >= 0; if (WINLO) ok = ok && rel < 512;
;             float v = s[kt][i]; if (LUTB) v += C.lut[C.h * 129 + (rel < 0 ? 0 : (rel < 128 ? rel : 128))];
;             s[kt][i] = ok ? v : NEG_INF; }
; }
; DEV void attn_unit_mfma(Frame& F, int qg, int kv) {
;     ...
;         const int j = lst[1 + i]; const unsigned byte = (msk[2 * j + (w >> 2)] >> (8 * (w & 3))) & 0xffu;
;         const bool a0 = (byte & 0xfu) != 0u, a1 = (byte & 0xf0u) != 0u;
;         if (a0 || a1) {
;             const bool near = j >= cur - 2; const float bi = near ? 0.f : C.b31;
;             const bool c0 = ((byte >> (C.n >> 2)) & 1u) != 0u, c1 = ((byte >> (4 + (C.n >> 2))) & 1u) != 0u;
;     ...
;             if (a0 && a1) SEL_BODY(true, true); else if (a0) SEL_BODY(true, false); else SEL_BODY(false, true);
.Lmy_orig_0:
	s_and_b32 s9, s8, 15
	s_cmp_eq_u32 s9, 0
	s_cselect_b64 s[14:15], -1, 0
	s_and_b32 s9, s8, 0xf0
	s_cmp_eq_u32 s9, 0
	s_cselect_b64 s[12:13], -1, 0
	s_cmp_ge_i32 s29, s22
	s_cselect_b64 s[18:19], -1, 0
	s_cmp_lt_i32 s29, s22
	v_and_b32_e32 v66, s8, v206
	s_cselect_b64 vcc, -1, 0
	v_cmp_ne_u32_e64 s[10:11], 0, v66
	v_and_b32_e32 v66, s8, v207
	s_or_b64 s[16:17], s[14:15], s[12:13]
	v_cndmask_b32_e32 v214, 0, v175, vcc
	v_cmp_ne_u32_e64 s[8:9], 0, v66
	s_mov_b64 s[12:13], -1
	s_and_b64 vcc, exec, s[16:17]
	s_cbranch_vccz .LBB0_1186
	v_add3_u32 v66, s27, v199, v198
	v_add3_u32 v67, s27, v197, v198
	ds_read_b128 v[70:73], v66
	ds_read_b128 v[74:77], v66 offset:2048
	ds_read_b128 v[90:93], v67
	ds_read_b128 v[78:81], v67 offset:2048
	ds_read_b128 v[82:85], v66 offset:4096
	ds_read_b128 v[86:89], v66 offset:6144
	ds_read_b128 v[94:97], v67 offset:4096
	ds_read_b128 v[66:69], v67 offset:6144
	s_and_b64 vcc, exec, s[14:15]
	s_cbranch_vccz .LBB0_1180
	v_cmp_eq_f32_e64 s[12:13], s3, v212
	s_nop 1
	v_cndmask_b32_e64 v98, v212, 0, s[12:13]
	v_sub_f32_e32 v98, v214, v98
	v_cndmask_b32_e64 v102, v173, v98, s[8:9]
	v_mov_b32_e32 v103, v102
	v_mov_b32_e32 v104, v102
	v_mov_b32_e32 v105, v102
	s_andn2_b64 vcc, exec, s[18:19]
	s_waitcnt lgkmcnt(0)
	v_mfma_f32_16x16x32_bf16 v[98:101], v[70:73], v[10:13], v[102:105]
	v_mfma_f32_16x16x32_bf16 v[110:113], v[90:93], v[14:17], v[98:101]
	v_mfma_f32_16x16x32_bf16 v[98:101], v[74:77], v[10:13], v[102:105]
	v_mfma_f32_16x16x32_bf16 v[106:109], v[78:81], v[14:17], v[98:101]
	v_mfma_f32_16x16x32_bf16 v[98:101], v[82:85], v[10:13], v[102:105]
	v_mfma_f32_16x16x32_bf16 v[102:105], v[86:89], v[10:13], v[102:105]
	v_mfma_f32_16x16x32_bf16 v[98:101], v[94:97], v[14:17], v[98:101]
	v_mfma_f32_16x16x32_bf16 v[102:105], v[66:69], v[14:17], v[102:105]
	s_cbranch_vccnz .LBB0_1177
	s_lshl_b32 s14, s29, 6
	v_subrev_u32_e32 v122, s14, v144
	v_sub_u32_e32 v123, v122, v20
	v_add_u32_e32 v124, v122, v208
	v_add_u32_e32 v125, -3, v123
	v_add_u32_e32 v126, -2, v123
	v_subrev_u32_e32 v127, 17, v123
	v_add_u32_e32 v128, -16, v123
	v_subrev_u32_e32 v129, 33, v123
	v_subrev_u32_e32 v130, 32, v123
	v_med3_i32 v114, v123, 0, v172
	v_med3_i32 v115, v124, 0, v172
	v_med3_i32 v116, v126, 0, v172
	v_med3_i32 v117, v125, 0, v172
	v_med3_i32 v118, v128, 0, v172
	v_med3_i32 v119, v127, 0, v172
	v_med3_i32 v120, v130, 0, v172
	v_med3_i32 v121, v129, 0, v172
	v_lshl_add_u32 v114, v114, 2, v174
	v_lshl_add_u32 v115, v115, 2, v174
	v_lshl_add_u32 v116, v116, 2, v174
	v_lshl_add_u32 v117, v117, 2, v174
	v_lshl_add_u32 v118, v118, 2, v174
	v_lshl_add_u32 v119, v119, 2, v174
	v_lshl_add_u32 v120, v120, 2, v174
	v_lshl_add_u32 v121, v121, 2, v174
	ds_read_b32 v114, v114
	ds_read_b32 v115, v115
	ds_read_b32 v116, v116
	ds_read_b32 v117, v117
	ds_read_b32 v118, v118
	ds_read_b32 v119, v119
	ds_read_b32 v120, v120
	ds_read_b32 v121, v121
	s_waitcnt lgkmcnt(0)
	v_pk_add_f32 v[110:111], v[110:111], v[114:115]
	v_cmp_lt_i32_e32 vcc, -1, v124
	v_pk_add_f32 v[112:113], v[112:113], v[116:117]
	v_sub_u32_e32 v116, v122, v158
	v_cndmask_b32_e32 v111, v173, v111, vcc
	v_cmp_lt_i32_e32 vcc, -1, v123
	v_sub_u32_e32 v117, v122, v1
	v_subrev_u32_e32 v124, 49, v123
	v_cndmask_b32_e32 v110, v173, v110, vcc
	v_cmp_lt_i32_e32 vcc, -1, v125
	v_subrev_u32_e32 v125, 48, v123
	v_add_u32_e32 v131, -16, v116
	v_cndmask_b32_e32 v113, v173, v113, vcc
	v_cmp_lt_i32_e32 vcc, -1, v126
	v_add_u32_e32 v126, -16, v117
	v_subrev_u32_e32 v132, 32, v117
	v_subrev_u32_e32 v133, 32, v116
	v_subrev_u32_e32 v135, 48, v116
	v_med3_i32 v114, v125, 0, v172
	v_med3_i32 v115, v124, 0, v172
	v_med3_i32 v122, v131, 0, v172
	v_med3_i32 v123, v126, 0, v172
	v_pk_add_f32 v[106:107], v[106:107], v[118:119]
	v_med3_i32 v118, v133, 0, v172
	v_med3_i32 v119, v132, 0, v172
	v_subrev_u32_e32 v134, 48, v117
	v_med3_i32 v116, v135, 0, v172
	v_lshl_add_u32 v114, v114, 2, v174
	v_lshl_add_u32 v115, v115, 2, v174
	v_lshl_add_u32 v122, v122, 2, v174
	v_lshl_add_u32 v123, v123, 2, v174
	v_lshl_add_u32 v118, v118, 2, v174
	v_lshl_add_u32 v119, v119, 2, v174
	v_lshl_add_u32 v136, v116, 2, v174
	v_med3_i32 v116, v134, 0, v172
	v_lshl_add_u32 v137, v116, 2, v174
	ds_read_b32 v114, v114
	ds_read_b32 v115, v115
	ds_read_b32 v116, v122
	ds_read_b32 v117, v123
	ds_read_b32 v118, v118
	ds_read_b32 v119, v119
	ds_read_b32 v122, v136
	ds_read_b32 v123, v137
	v_cndmask_b32_e32 v112, v173, v112, vcc
	s_waitcnt lgkmcnt(0)
	v_pk_add_f32 v[108:109], v[108:109], v[116:117]
	v_cmp_lt_i32_e32 vcc, -1, v126
	v_pk_add_f32 v[100:101], v[100:101], v[118:119]
	v_pk_add_f32 v[98:99], v[98:99], v[120:121]
	v_cndmask_b32_e32 v109, v173, v109, vcc
	v_cmp_lt_i32_e32 vcc, -1, v131
	v_pk_add_f32 v[104:105], v[104:105], v[122:123]
	v_pk_add_f32 v[102:103], v[102:103], v[114:115]
	v_cndmask_b32_e32 v108, v173, v108, vcc
	v_cmp_lt_i32_e32 vcc, -1, v127
	s_nop 1
	v_cndmask_b32_e32 v107, v173, v107, vcc
	v_cmp_lt_i32_e32 vcc, -1, v128
	s_nop 1
	v_cndmask_b32_e32 v106, v173, v106, vcc
	v_cmp_lt_i32_e32 vcc, -1, v132
	s_nop 1
	v_cndmask_b32_e32 v101, v173, v101, vcc
	v_cmp_lt_i32_e32 vcc, -1, v133
	s_nop 1
	v_cndmask_b32_e32 v100, v173, v100, vcc
	v_cmp_lt_i32_e32 vcc, -1, v129
	s_nop 1
	v_cndmask_b32_e32 v99, v173, v99, vcc
	v_cmp_lt_i32_e32 vcc, -1, v130
	s_nop 1
	v_cndmask_b32_e32 v98, v173, v98, vcc
	v_cmp_lt_i32_e32 vcc, -1, v134
	s_nop 1
	v_cndmask_b32_e32 v105, v173, v105, vcc
	v_cmp_lt_i32_e32 vcc, -1, v135
	s_nop 1
	v_cndmask_b32_e32 v104, v173, v104, vcc
	v_cmp_lt_i32_e32 vcc, -1, v124
	s_nop 1
	v_cndmask_b32_e32 v103, v173, v103, vcc
	v_cmp_lt_i32_e32 vcc, -1, v125
	s_nop 1
	v_cndmask_b32_e32 v102, v173, v102, vcc

; DEV void qk64(const LAS unsigned char* Kb, const AttnCtx& C, const ab8 (&qf)[2][2], f32x4 (&s)[2][4], float init0, float init1, bool a0, bool a1) {
;     ab8 k0[4], k1[4];
; #pragma unroll
;     for (int kt = 0; kt < 4; ++kt) { k0[kt] = *(const LAS ab8*)(Kb + swz(16 * kt + C.n, C.q4)); k1[kt] = *(const LAS ab8*)(Kb + swz(16 * kt + C.n, 4 + C.q4)); }
;     __builtin_amdgcn_sched_barrier(0);
; #pragma unroll
;     for (int kt = 0; kt < 4; ++kt) {
;         if (a0) { f32x4 c = {init0, init0, init0, init0}; c = __builtin_amdgcn_mfma_f32_16x16x32_bf16(k0[kt], qf[0][0], c, 0, 0, 0); s[0][kt] = __builtin_amdgcn_mfma_f32_16x16x32_bf16(k1[kt], qf[0][1], c, 0, 0, 0); }
;         if (a1) { f32x4 c = {init1, init1, init1, init1}; c = __builtin_amdgcn_mfma_f32_16x16x32_bf16(k0[kt], qf[1][0], c, 0, 0, 0); s[1][kt] = __builtin_amdgcn_mfma_f32_16x16x32_bf16(k1[kt], qf[1][1], c, 0, 0, 0); }
; DEV void ref_step(f32x4 (&s)[4], float& m, f32x4 (&O)[4], f32x4& L, ab8 (&pf)[2], bool colact) {
;     ...
;     const bool slow = (colact && m == NEG_INF) || mx > 64.f;
;     if (__any(slow)) {
;         mx = fmaxf(mx, __shfl_xor(mx, 16)); mx = fmaxf(mx, __shfl_xor(mx, 32));
;         const bool un = (m == NEG_INF);
;         const float d = (mx == NEG_INF) ? 0.f : (un ? mx : fmaxf(mx, 0.f));
;         const float sc = un ? 1.f : __builtin_amdgcn_exp2f(-d);
; #pragma unroll
;         for (int kt = 0; kt < 4; ++kt) s[kt] = s[kt] - d;
; #pragma unroll
;         for (int dt = 0; dt < 4; ++dt) O[dt] = O[dt] * sc;
;         L = L * sc;
;         m = un ? ((mx == NEG_INF) ? NEG_INF : mx) : m + d;
;     }
; #pragma unroll
;     for (int kt = 0; kt < 4; ++kt)
; #pragma unroll
;         for (int i = 0; i < 4; ++i) s[kt][i] = __builtin_amdgcn_exp2f(s[kt][i]);
; #pragma unroll
;     for (int j = 0; j < 2; ++j) { v4u w; w.x = cvtpk(s[2 * j][0], s[2 * j][1]); w.y = cvtpk(s[2 * j][2], s[2 * j][3]); w.z = cvtpk(s[2 * j + 1][0], s[2 * j + 1][1]); w.w = cvtpk(s[2 * j + 1][2], s[2 * j + 1][3]); pf[j] = __builtin_bit_cast(ab8, w); }
; }
; template <bool PV, bool WITHL>
; DEV void pv64(const LAS unsigned char* Vb, const AttnCtx& C, const ab8 (&pf)[2][2], f32x4 (&O)[2][4], f32x4 (&L)[2], bool a0, bool a1) {
;     if (PV) {
;         const int vr = 4 * C.q4 + (C.n >> 2), vc = (C.n & 3) >> 1, vs = 8 * (C.n & 1);
;         ab8 vf[4][2];
; #pragma unroll
;         for (int dt = 0; dt < 4; ++dt)
; #pragma unroll
.LBB0_1196:
	s_add_i32 s8, s28, -1
	s_cmp_ge_i32 s8, s23
	s_cbranch_scc1 .LBB0_1222
	s_waitcnt lgkmcnt(0)
	s_and_b32 s29, s99, 0xffff
	s_lshr_b32 s8, s99, 16
	s_and_b32 s9, s8, 0xff
	s_cmp_eq_u32 s9, 0
	s_cbranch_scc1 .LBB0_1222
	s_cmp_ge_i32 s29, s22
	s_cbranch_scc1 .Lmy_orig_1
	s_and_b32 s9, s8, 15
	s_and_b32 s10, s8, 0xf0
	s_cmp_lg_u32 s9, 0
	s_cselect_b32 s11, 1, 0
	s_cmp_lg_u32 s10, 0
	s_cselect_b32 s12, 1, 0
	s_add_i32 s13, s11, s12
	s_cmp_eq_u32 s13, 2
	s_cbranch_scc1 .Lmy_orig_1
	s_cmp_eq_u32 s11, 1
	s_cbranch_scc0 .Lmy_f1_1
	v_add3_u32 v228, s27, v199, v198
	v_add3_u32 v229, s27, v197, v198
	ds_read_b128 v[66:69], v228 offset:16384
	ds_read_b128 v[70:73], v229 offset:16384
	ds_read_b128 v[74:77], v228 offset:18432
	ds_read_b128 v[78:81], v229 offset:18432
	ds_read_b128 v[82:85], v228 offset:20480
	ds_read_b128 v[86:89], v229 offset:20480
	ds_read_b128 v[90:93], v228 offset:22528
	ds_read_b128 v[94:97], v229 offset:22528
	v_and_b32_e32 v239, s8, v206
	v_cmp_ne_u32_e64 s[10:11], 0, v239
	v_cmp_eq_f32_e64 s[12:13], s3, v213
	v_add_u32_e32 v234, s27, v200
	v_add3_u32 v235, v234, v201, v209
	v_add3_u32 v236, v234, v202, v209
	v_cndmask_b32_e64 v230, v213, 0, s[12:13]
	v_sub_f32_e32 v230, v175, v230
	v_add3_u32 v237, v234, v203, v209
	v_add3_u32 v238, v234, v204, v209
	v_cndmask_b32_e64 v230, v173, v230, s[10:11]
	s_and_b64 s[12:13], s[10:11], s[12:13]
	v_mov_b32_e32 v231, v230
	v_mov_b32_e32 v232, v230
	v_mov_b32_e32 v233, v230
	s_waitcnt lgkmcnt(0)
	v_mfma_f32_16x16x32_bf16 v[66:69], v[66:69], v[2:5], v[230:233]
	v_mfma_f32_16x16x32_bf16 v[74:77], v[74:77], v[2:5], v[230:233]
	v_mfma_f32_16x16x32_bf16 v[82:85], v[82:85], v[2:5], v[230:233]
	v_mfma_f32_16x16x32_bf16 v[90:93], v[90:93], v[2:5], v[230:233]
	v_mfma_f32_16x16x32_bf16 v[66:69], v[70:73], v[6:9], v[66:69]
	v_mfma_f32_16x16x32_bf16 v[74:77], v[78:81], v[6:9], v[74:77]
	v_mfma_f32_16x16x32_bf16 v[82:85], v[86:89], v[6:9], v[82:85]
	v_mfma_f32_16x16x32_bf16 v[90:93], v[94:97], v[6:9], v[90:93]
	ds_read_b64_tr_b16 v[98:99], v235 offset:24576
	ds_read_b64_tr_b16 v[100:101], v235 offset:26624
	ds_read_b64_tr_b16 v[102:103], v235 offset:28672
	ds_read_b64_tr_b16 v[104:105], v235 offset:30720
	ds_read_b64_tr_b16 v[106:107], v236 offset:24576
	ds_read_b64_tr_b16 v[108:109], v236 offset:26624
	ds_read_b64_tr_b16 v[110:111], v236 offset:28672
	ds_read_b64_tr_b16 v[112:113], v236 offset:30720
	ds_read_b64_tr_b16 v[114:115], v237 offset:24576
	ds_read_b64_tr_b16 v[116:117], v237 offset:26624
	ds_read_b64_tr_b16 v[118:119], v237 offset:28672
	ds_read_b64_tr_b16 v[120:121], v237 offset:30720
	ds_read_b64_tr_b16 v[122:123], v238 offset:24576
	ds_read_b64_tr_b16 v[124:125], v238 offset:26624
	ds_read_b64_tr_b16 v[126:127], v238 offset:28672
	ds_read_b64_tr_b16 v[128:129], v238 offset:30720
	v_max3_f32 v239, v66, v67, v68
	v_max3_f32 v240, v69, v74, v75
	v_max3_f32 v241, v76, v77, v82
	v_max3_f32 v242, v83, v84, v85
	v_max3_f32 v239, v239, v240, v90
	v_max3_f32 v241, v241, v242, v91
	v_max3_f32 v239, v239, v92, v93
	v_max_f32_e32 v239, v239, v241
	v_cmp_lt_f32_e32 vcc, s96, v239
	s_or_b64 s[12:13], s[12:13], vcc
	s_cmp_lg_u64 s[12:13], 0
	s_cbranch_scc1 .Lmy_slow_0_1
	v_exp_f32_e32 v66, v66
	v_exp_f32_e32 v67, v67
	v_exp_f32_e32 v68, v68
	v_exp_f32_e32 v69, v69
	v_exp_f32_e32 v74, v74
	v_exp_f32_e32 v75, v75
	v_exp_f32_e32 v76, v76
	v_exp_f32_e32 v77, v77
	v_exp_f32_e32 v82, v82
	v_exp_f32_e32 v83, v83
	v_exp_f32_e32 v84, v84
	v_exp_f32_e32 v85, v85
	v_exp_f32_e32 v90, v90
	v_exp_f32_e32 v91, v91
	v_exp_f32_e32 v92, v92
	v_exp_f32_e32 v93, v93
	v_cvt_pk_bf16_f32 v130, v66, v67
	v_cvt_pk_bf16_f32 v131, v68, v69
	v_cvt_pk_bf16_f32 v132, v74, v75
	v_cvt_pk_bf16_f32 v133, v76, v77
	v_cvt_pk_bf16_f32 v134, v82, v83
	v_cvt_pk_bf16_f32 v135, v84, v85
	v_cvt_pk_bf16_f32 v136, v90, v91
	v_cvt_pk_bf16_f32 v137, v92, v93
	s_nop 1
	s_waitcnt lgkmcnt(12)
	v_mfma_f32_16x16x32_bf16 v[62:65], v[98:101], v[130:133], v[62:65]
	v_mfma_f32_16x16x32_bf16 v[58:61], v[22:25], v[130:133], v[58:61]
	v_mfma_f32_16x16x32_bf16 v[62:65], v[102:105], v[134:137], v[62:65]
	s_waitcnt lgkmcnt(8)
	v_mfma_f32_16x16x32_bf16 v[54:57], v[106:109], v[130:133], v[54:57]
	v_mfma_f32_16x16x32_bf16 v[54:57], v[110:113], v[134:137], v[54:57]
	s_waitcnt lgkmcnt(4)
	v_mfma_f32_16x16x32_bf16 v[50:53], v[114:117], v[130:133], v[50:53]
	v_mfma_f32_16x16x32_bf16 v[58:61], v[22:25], v[134:137], v[58:61]
	v_mfma_f32_16x16x32_bf16 v[50:53], v[118:121], v[134:137], v[50:53]
	s_waitcnt lgkmcnt(0)
	v_mfma_f32_16x16x32_bf16 v[46:49], v[122:125], v[130:133], v[46:49]
	v_mfma_f32_16x16x32_bf16 v[46:49], v[126:129], v[134:137], v[46:49]
	s_nop 7
	s_branch .LBB0_1222

; DEV void qk64(const LAS unsigned char* Kb, const AttnCtx& C, const ab8 (&qf)[2][2], f32x4 (&s)[2][4], float init0, float init1, bool a0, bool a1) {
;     ab8 k0[4], k1[4];
; #pragma unroll
;     for (int kt = 0; kt < 4; ++kt) { k0[kt] = *(const LAS ab8*)(Kb + swz(16 * kt + C.n, C.q4)); k1[kt] = *(const LAS ab8*)(Kb + swz(16 * kt + C.n, 4 + C.q4)); }
;     __builtin_amdgcn_sched_barrier(0);
; #pragma unroll
;     for (int kt = 0; kt < 4; ++kt) {
;         if (a0) { f32x4 c = {init0, init0, init0, init0}; c = __builtin_amdgcn_mfma_f32_16x16x32_bf16(k0[kt], qf[0][0], c, 0, 0, 0); s[0][kt] = __builtin_amdgcn_mfma_f32_16x16x32_bf16(k1[kt], qf[0][1], c, 0, 0, 0); }
;         if (a1) { f32x4 c = {init1, init1, init1, init1}; c = __builtin_amdgcn_mfma_f32_16x16x32_bf16(k0[kt], qf[1][0], c, 0, 0, 0); s[1][kt] = __builtin_amdgcn_mfma_f32_16x16x32_bf16(k1[kt], qf[1][1], c, 0, 0, 0); }
; DEV void ref_step(f32x4 (&s)[4], float& m, f32x4 (&O)[4], f32x4& L, ab8 (&pf)[2], bool colact) {
;     ...
;     const bool slow = (colact && m == NEG_INF) || mx > 64.f;
;     if (__any(slow)) {
;         mx = fmaxf(mx, __shfl_xor(mx, 16)); mx = fmaxf(mx, __shfl_xor(mx, 32));
;         const bool un = (m == NEG_INF);
;         const float d = (mx == NEG_INF) ? 0.f : (un ? mx : fmaxf(mx, 0.f));
;         const float sc = un ? 1.f : __builtin_amdgcn_exp2f(-d);
; #pragma unroll
;         for (int kt = 0; kt < 4; ++kt) s[kt] = s[kt] - d;
; #pragma unroll
;         for (int dt = 0; dt < 4; ++dt) O[dt] = O[dt] * sc;
;         L = L * sc;
;         m = un ? ((mx == NEG_INF) ? NEG_INF : mx) : m + d;
;     }
; #pragma unroll
;     for (int kt = 0; kt < 4; ++kt)
; #pragma unroll
;         for (int i = 0; i < 4; ++i) s[kt][i] = __builtin_amdgcn_exp2f(s[kt][i]);
; #pragma unroll
;     for (int j = 0; j < 2; ++j) { v4u w; w.x = cvtpk(s[2 * j][0], s[2 * j][1]); w.y = cvtpk(s[2 * j][2], s[2 * j][3]); w.z = cvtpk(s[2 * j + 1][0], s[2 * j + 1][1]); w.w = cvtpk(s[2 * j + 1][2], s[2 * j + 1][3]); pf[j] = __builtin_bit_cast(ab8, w); }
; }
; template <bool PV, bool WITHL>
; DEV void pv64(const LAS unsigned char* Vb, const AttnCtx& C, const ab8 (&pf)[2][2], f32x4 (&O)[2][4], f32x4 (&L)[2], bool a0, bool a1) {
;     if (PV) {
;         const int vr = 4 * C.q4 + (C.n >> 2), vc = (C.n & 3) >> 1, vs = 8 * (C.n & 1);
;         ab8 vf[4][2];
; #pragma unroll
;         for (int dt = 0; dt < 4; ++dt)
; #pragma unroll
.Lmy_f1_1:
	v_add3_u32 v228, s27, v199, v198
	v_add3_u32 v229, s27, v197, v198
	ds_read_b128 v[66:69], v228 offset:16384
	ds_read_b128 v[70:73], v229 offset:16384
	ds_read_b128 v[74:77], v228 offset:18432
	ds_read_b128 v[78:81], v229 offset:18432
	ds_read_b128 v[82:85], v228 offset:20480
	ds_read_b128 v[86:89], v229 offset:20480
	ds_read_b128 v[90:93], v228 offset:22528
	ds_read_b128 v[94:97], v229 offset:22528
	v_and_b32_e32 v239, s8, v207
	v_cmp_ne_u32_e64 s[10:11], 0, v239
	v_cmp_eq_f32_e64 s[12:13], s3, v212
	v_add_u32_e32 v234, s27, v200
	v_add3_u32 v235, v234, v201, v209
	v_add3_u32 v236, v234, v202, v209
	v_cndmask_b32_e64 v230, v212, 0, s[12:13]
	v_sub_f32_e32 v230, v175, v230
	v_add3_u32 v237, v234, v203, v209
	v_add3_u32 v238, v234, v204, v209
	v_cndmask_b32_e64 v230, v173, v230, s[10:11]
	s_and_b64 s[12:13], s[10:11], s[12:13]
	v_mov_b32_e32 v231, v230
	v_mov_b32_e32 v232, v230
	v_mov_b32_e32 v233, v230
	s_waitcnt lgkmcnt(0)
	v_mfma_f32_16x16x32_bf16 v[66:69], v[66:69], v[10:13], v[230:233]
	v_mfma_f32_16x16x32_bf16 v[74:77], v[74:77], v[10:13], v[230:233]
	v_mfma_f32_16x16x32_bf16 v[82:85], v[82:85], v[10:13], v[230:233]
	v_mfma_f32_16x16x32_bf16 v[90:93], v[90:93], v[10:13], v[230:233]
	v_mfma_f32_16x16x32_bf16 v[66:69], v[70:73], v[14:17], v[66:69]
	v_mfma_f32_16x16x32_bf16 v[74:77], v[78:81], v[14:17], v[74:77]
	v_mfma_f32_16x16x32_bf16 v[82:85], v[86:89], v[14:17], v[82:85]
	v_mfma_f32_16x16x32_bf16 v[90:93], v[94:97], v[14:17], v[90:93]
	ds_read_b64_tr_b16 v[98:99], v235 offset:24576
	ds_read_b64_tr_b16 v[100:101], v235 offset:26624
	ds_read_b64_tr_b16 v[102:103], v235 offset:28672
	ds_read_b64_tr_b16 v[104:105], v235 offset:30720
	ds_read_b64_tr_b16 v[106:107], v236 offset:24576
	ds_read_b64_tr_b16 v[108:109], v236 offset:26624
	ds_read_b64_tr_b16 v[110:111], v236 offset:28672
	ds_read_b64_tr_b16 v[112:113], v236 offset:30720
	ds_read_b64_tr_b16 v[114:115], v237 offset:24576
	ds_read_b64_tr_b16 v[116:117], v237 offset:26624
	ds_read_b64_tr_b16 v[118:119], v237 offset:28672
	ds_read_b64_tr_b16 v[120:121], v237 offset:30720
	ds_read_b64_tr_b16 v[122:123], v238 offset:24576
	ds_read_b64_tr_b16 v[124:125], v238 offset:26624
	ds_read_b64_tr_b16 v[126:127], v238 offset:28672
	ds_read_b64_tr_b16 v[128:129], v238 offset:30720
	v_max3_f32 v239, v66, v67, v68
	v_max3_f32 v240, v69, v74, v75
	v_max3_f32 v241, v76, v77, v82
	v_max3_f32 v242, v83, v84, v85
	v_max3_f32 v239, v239, v240, v90
	v_max3_f32 v241, v241, v242, v91
	v_max3_f32 v239, v239, v92, v93
	v_max_f32_e32 v239, v239, v241
	v_cmp_lt_f32_e32 vcc, s96, v239
	s_or_b64 s[12:13], s[12:13], vcc
	s_cmp_lg_u64 s[12:13], 0
	s_cbranch_scc1 .Lmy_slow_1_1
	v_exp_f32_e32 v66, v66
	v_exp_f32_e32 v67, v67
	v_exp_f32_e32 v68, v68
	v_exp_f32_e32 v69, v69
	v_exp_f32_e32 v74, v74
	v_exp_f32_e32 v75, v75
	v_exp_f32_e32 v76, v76
	v_exp_f32_e32 v77, v77
	v_exp_f32_e32 v82, v82
	v_exp_f32_e32 v83, v83
	v_exp_f32_e32 v84, v84
	v_exp_f32_e32 v85, v85
	v_exp_f32_e32 v90, v90
	v_exp_f32_e32 v91, v91
	v_exp_f32_e32 v92, v92
	v_exp_f32_e32 v93, v93
	v_cvt_pk_bf16_f32 v130, v66, v67
	v_cvt_pk_bf16_f32 v131, v68, v69
	v_cvt_pk_bf16_f32 v132, v74, v75
	v_cvt_pk_bf16_f32 v133, v76, v77
	v_cvt_pk_bf16_f32 v134, v82, v83
	v_cvt_pk_bf16_f32 v135, v84, v85
	v_cvt_pk_bf16_f32 v136, v90, v91
	v_cvt_pk_bf16_f32 v137, v92, v93
	s_nop 1
	s_waitcnt lgkmcnt(12)
	v_mfma_f32_16x16x32_bf16 v[38:41], v[98:101], v[130:133], v[38:41]
	v_mfma_f32_16x16x32_bf16 v[42:45], v[22:25], v[130:133], v[42:45]
	v_mfma_f32_16x16x32_bf16 v[38:41], v[102:105], v[134:137], v[38:41]
	s_waitcnt lgkmcnt(8)
	v_mfma_f32_16x16x32_bf16 v[34:37], v[106:109], v[130:133], v[34:37]
	v_mfma_f32_16x16x32_bf16 v[34:37], v[110:113], v[134:137], v[34:37]
	s_waitcnt lgkmcnt(4)
	v_mfma_f32_16x16x32_bf16 v[30:33], v[114:117], v[130:133], v[30:33]
	v_mfma_f32_16x16x32_bf16 v[42:45], v[22:25], v[134:137], v[42:45]
	v_mfma_f32_16x16x32_bf16 v[30:33], v[118:121], v[134:137], v[30:33]
	s_waitcnt lgkmcnt(0)
	v_mfma_f32_16x16x32_bf16 v[26:29], v[122:125], v[130:133], v[26:29]
	v_mfma_f32_16x16x32_bf16 v[26:29], v[126:129], v[134:137], v[26:29]
	s_nop 7
	s_branch .LBB0_1222

; #define NEG_INF (-__builtin_inff())
; template <bool LUTB, bool WINLO>
; DEV void mask_bias(f32x4 (&s)[4], const AttnCtx& C, int t, int p0, int pstep, bool colok) {
; #pragma unroll
;     for (int kt = 0; kt < 4; ++kt)
; #pragma unroll
;         for (int i = 0; i < 4; ++i) { const int rel = t - (p0 + pstep * (16 * kt + 4 * C.q4 + i));
;             bool ok = colok && rel >= 0; if (WINLO) ok = ok && rel < 512;
;             float v = s[kt][i]; if (LUTB) v += C.lut[C.h * 129 + (rel < 0 ? 0 : (rel < 128 ? rel : 128))];
;             s[kt][i] = ok ? v : NEG_INF; }
; }
; DEV void attn_unit_mfma(Frame& F, int qg, int kv) {
;     ...
;         const int j = lst[1 + i]; const unsigned byte = (msk[2 * j + (w >> 2)] >> (8 * (w & 3))) & 0xffu;
;         const bool a0 = (byte & 0xfu) != 0u, a1 = (byte & 0xf0u) != 0u;
;         if (a0 || a1) {
;             const bool near = j >= cur - 2; const float bi = near ? 0.f : C.b31;
;             const bool c0 = ((byte >> (C.n >> 2)) & 1u) != 0u, c1 = ((byte >> (4 + (C.n >> 2))) & 1u) != 0u;
;     ...
;             if (a0 && a1) SEL_BODY(true, true); else if (a0) SEL_BODY(true, false); else SEL_BODY(false, true);
.Lmy_orig_1:
	s_and_b32 s9, s8, 15
	s_cmp_eq_u32 s9, 0
	s_cselect_b64 s[12:13], -1, 0
	s_cmp_lg_u32 s9, 0
	s_cselect_b64 s[14:15], -1, 0
	s_and_b32 s9, s8, 0xf0
	s_cmp_lg_u32 s9, 0
	s_cselect_b64 s[16:17], -1, 0
	s_cmp_ge_i32 s29, s22
	s_cselect_b64 s[18:19], -1, 0
	s_cmp_lt_i32 s29, s22
	v_and_b32_e32 v66, s8, v206
	s_cselect_b64 vcc, -1, 0
	v_cmp_ne_u32_e64 s[10:11], 0, v66
	v_and_b32_e32 v66, s8, v207
	s_and_b64 s[16:17], s[14:15], s[16:17]
	v_cndmask_b32_e32 v214, 0, v175, vcc
	v_cmp_ne_u32_e64 s[8:9], 0, v66
	s_mov_b64 s[14:15], -1
	s_and_b64 vcc, exec, s[16:17]
	s_cbranch_vccnz .LBB0_1212
	v_add3_u32 v66, s27, v199, v198
	v_add3_u32 v67, s27, v197, v198
	ds_read_b128 v[70:73], v66 offset:16384
	ds_read_b128 v[74:77], v66 offset:18432
	ds_read_b128 v[90:93], v67 offset:16384
	ds_read_b128 v[78:81], v67 offset:18432
	ds_read_b128 v[82:85], v66 offset:20480
	ds_read_b128 v[86:89], v66 offset:22528
	ds_read_b128 v[94:97], v67 offset:20480
	ds_read_b128 v[66:69], v67 offset:22528
	s_andn2_b64 vcc, exec, s[12:13]
	s_mov_b64 s[12:13], -1
	s_cbranch_vccnz .LBB0_1205
	v_cmp_eq_f32_e64 s[12:13], s3, v212
	s_nop 1
	v_cndmask_b32_e64 v98, v212, 0, s[12:13]
	v_sub_f32_e32 v98, v214, v98
	v_cndmask_b32_e64 v102, v173, v98, s[8:9]
	v_mov_b32_e32 v103, v102
	v_mov_b32_e32 v104, v102
	v_mov_b32_e32 v105, v102
	s_andn2_b64 vcc, exec, s[18:19]
	s_waitcnt lgkmcnt(0)
	v_mfma_f32_16x16x32_bf16 v[98:101], v[70:73], v[10:13], v[102:105]
	v_mfma_f32_16x16x32_bf16 v[110:113], v[90:93], v[14:17], v[98:101]
	v_mfma_f32_16x16x32_bf16 v[98:101], v[74:77], v[10:13], v[102:105]
	v_mfma_f32_16x16x32_bf16 v[106:109], v[78:81], v[14:17], v[98:101]
	v_mfma_f32_16x16x32_bf16 v[98:101], v[82:85], v[10:13], v[102:105]
	v_mfma_f32_16x16x32_bf16 v[102:105], v[86:89], v[10:13], v[102:105]
	v_mfma_f32_16x16x32_bf16 v[98:101], v[94:97], v[14:17], v[98:101]
	v_mfma_f32_16x16x32_bf16 v[102:105], v[66:69], v[14:17], v[102:105]
	s_cbranch_vccnz .LBB0_1202
	s_lshl_b32 s14, s29, 6
	v_subrev_u32_e32 v122, s14, v144
	v_sub_u32_e32 v123, v122, v20
	v_add_u32_e32 v124, v122, v208
	v_add_u32_e32 v125, -3, v123
	v_add_u32_e32 v126, -2, v123
	v_subrev_u32_e32 v127, 17, v123
	v_add_u32_e32 v128, -16, v123
	v_subrev_u32_e32 v129, 33, v123
	v_subrev_u32_e32 v130, 32, v123
	v_med3_i32 v114, v123, 0, v172
	v_med3_i32 v115, v124, 0, v172
	v_med3_i32 v116, v126, 0, v172
	v_med3_i32 v117, v125, 0, v172
	v_med3_i32 v118, v128, 0, v172
	v_med3_i32 v119, v127, 0, v172
	v_med3_i32 v120, v130, 0, v172
	v_med3_i32 v121, v129, 0, v172
	v_lshl_add_u32 v114, v114, 2, v174
	v_lshl_add_u32 v115, v115, 2, v174
	v_lshl_add_u32 v116, v116, 2, v174
	v_lshl_add_u32 v117, v117, 2, v174
	v_lshl_add_u32 v118, v118, 2, v174
	v_lshl_add_u32 v119, v119, 2, v174
	v_lshl_add_u32 v120, v120, 2, v174
	v_lshl_add_u32 v121, v121, 2, v174
	ds_read_b32 v114, v114
	ds_read_b32 v115, v115
	ds_read_b32 v116, v116
	ds_read_b32 v117, v117
	ds_read_b32 v118, v118
	ds_read_b32 v119, v119
	ds_read_b32 v120, v120
	ds_read_b32 v121, v121
	s_waitcnt lgkmcnt(0)
	v_pk_add_f32 v[110:111], v[110:111], v[114:115]
	v_cmp_lt_i32_e32 vcc, -1, v124
	v_pk_add_f32 v[112:113], v[112:113], v[116:117]
	v_sub_u32_e32 v116, v122, v158
	v_cndmask_b32_e32 v111, v173, v111, vcc
	v_cmp_lt_i32_e32 vcc, -1, v123
	v_sub_u32_e32 v117, v122, v1
	v_subrev_u32_e32 v124, 49, v123
	v_cndmask_b32_e32 v110, v173, v110, vcc
	v_cmp_lt_i32_e32 vcc, -1, v125
	v_subrev_u32_e32 v125, 48, v123
	v_add_u32_e32 v131, -16, v116
	v_cndmask_b32_e32 v113, v173, v113, vcc
	v_cmp_lt_i32_e32 vcc, -1, v126
	v_add_u32_e32 v126, -16, v117
	v_subrev_u32_e32 v132, 32, v117
	v_subrev_u32_e32 v133, 32, v116
	v_subrev_u32_e32 v135, 48, v116
	v_med3_i32 v114, v125, 0, v172
	v_med3_i32 v115, v124, 0, v172
	v_med3_i32 v122, v131, 0, v172
	v_med3_i32 v123, v126, 0, v172
	v_pk_add_f32 v[106:107], v[106:107], v[118:119]
	v_med3_i32 v118, v133, 0, v172
	v_med3_i32 v119, v132, 0, v172
	v_subrev_u32_e32 v134, 48, v117
	v_med3_i32 v116, v135, 0, v172
	v_lshl_add_u32 v114, v114, 2, v174
	v_lshl_add_u32 v115, v115, 2, v174
	v_lshl_add_u32 v122, v122, 2, v174
	v_lshl_add_u32 v123, v123, 2, v174
	v_lshl_add_u32 v118, v118, 2, v174
	v_lshl_add_u32 v119, v119, 2, v174
	v_lshl_add_u32 v136, v116, 2, v174
	v_med3_i32 v116, v134, 0, v172
	v_lshl_add_u32 v137, v116, 2, v174
	ds_read_b32 v114, v114
	ds_read_b32 v115, v115
	ds_read_b32 v116, v122
	ds_read_b32 v117, v123
	ds_read_b32 v118, v118
	ds_read_b32 v119, v119
	ds_read_b32 v122, v136
	ds_read_b32 v123, v137
	v_cndmask_b32_e32 v112, v173, v112, vcc
	s_waitcnt lgkmcnt(0)
	v_pk_add_f32 v[108:109], v[108:109], v[116:117]
	v_cmp_lt_i32_e32 vcc, -1, v126
	v_pk_add_f32 v[100:101], v[100:101], v[118:119]
	v_pk_add_f32 v[98:99], v[98:99], v[120:121]
	v_cndmask_b32_e32 v109, v173, v109, vcc
	v_cmp_lt_i32_e32 vcc, -1, v131
	v_pk_add_f32 v[104:105], v[104:105], v[122:123]
	v_pk_add_f32 v[102:103], v[102:103], v[114:115]
	v_cndmask_b32_e32 v108, v173, v108, vcc
	v_cmp_lt_i32_e32 vcc, -1, v127
	s_nop 1
	v_cndmask_b32_e32 v107, v173, v107, vcc
	v_cmp_lt_i32_e32 vcc, -1, v128
	s_nop 1
	v_cndmask_b32_e32 v106, v173, v106, vcc
	v_cmp_lt_i32_e32 vcc, -1, v132
	s_nop 1
	v_cndmask_b32_e32 v101, v173, v101, vcc
	v_cmp_lt_i32_e32 vcc, -1, v133
	s_nop 1
	v_cndmask_b32_e32 v100, v173, v100, vcc
	v_cmp_lt_i32_e32 vcc, -1, v129
	s_nop 1
	v_cndmask_b32_e32 v99, v173, v99, vcc
	v_cmp_lt_i32_e32 vcc, -1, v130
	s_nop 1
	v_cndmask_b32_e32 v98, v173, v98, vcc
	v_cmp_lt_i32_e32 vcc, -1, v134
	s_nop 1
	v_cndmask_b32_e32 v105, v173, v105, vcc
	v_cmp_lt_i32_e32 vcc, -1, v135
	s_nop 1
	v_cndmask_b32_e32 v104, v173, v104, vcc
	v_cmp_lt_i32_e32 vcc, -1, v124
	s_nop 1
	v_cndmask_b32_e32 v103, v173, v103, vcc
	v_cmp_lt_i32_e32 vcc, -1, v125
	s_nop 1
	v_cndmask_b32_e32 v102, v173, v102, vcc

; DEV void qk64(const LAS unsigned char* Kb, const AttnCtx& C, const ab8 (&qf)[2][2], f32x4 (&s)[2][4], float init0, float init1, bool a0, bool a1) {
;     ab8 k0[4], k1[4];
; #pragma unroll
;     for (int kt = 0; kt < 4; ++kt) { k0[kt] = *(const LAS ab8*)(Kb + swz(16 * kt + C.n, C.q4)); k1[kt] = *(const LAS ab8*)(Kb + swz(16 * kt + C.n, 4 + C.q4)); }
;     __builtin_amdgcn_sched_barrier(0);
; #pragma unroll
;     for (int kt = 0; kt < 4; ++kt) {
;         if (a0) { f32x4 c = {init0, init0, init0, init0}; c = __builtin_amdgcn_mfma_f32_16x16x32_bf16(k0[kt], qf[0][0], c, 0, 0, 0); s[0][kt] = __builtin_amdgcn_mfma_f32_16x16x32_bf16(k1[kt], qf[0][1], c, 0, 0, 0); }
;         if (a1) { f32x4 c = {init1, init1, init1, init1}; c = __builtin_amdgcn_mfma_f32_16x16x32_bf16(k0[kt], qf[1][0], c, 0, 0, 0); s[1][kt] = __builtin_amdgcn_mfma_f32_16x16x32_bf16(k1[kt], qf[1][1], c, 0, 0, 0); }
; DEV void ref_step(f32x4 (&s)[4], float& m, f32x4 (&O)[4], f32x4& L, ab8 (&pf)[2], bool colact) {
;     ...
;     const bool slow = (colact && m == NEG_INF) || mx > 64.f;
;     if (__any(slow)) {
;         mx = fmaxf(mx, __shfl_xor(mx, 16)); mx = fmaxf(mx, __shfl_xor(mx, 32));
;         const bool un = (m == NEG_INF);
;         const float d = (mx == NEG_INF) ? 0.f : (un ? mx : fmaxf(mx, 0.f));
;         const float sc = un ? 1.f : __builtin_amdgcn_exp2f(-d);
; #pragma unroll
;         for (int kt = 0; kt < 4; ++kt) s[kt] = s[kt] - d;
; #pragma unroll
;         for (int dt = 0; dt < 4; ++dt) O[dt] = O[dt] * sc;
;         L = L * sc;
;         m = un ? ((mx == NEG_INF) ? NEG_INF : mx) : m + d;
;     }
; #pragma unroll
;     for (int kt = 0; kt < 4; ++kt)
; #pragma unroll
;         for (int i = 0; i < 4; ++i) s[kt][i] = __builtin_amdgcn_exp2f(s[kt][i]);
; #pragma unroll
;     for (int j = 0; j < 2; ++j) { v4u w; w.x = cvtpk(s[2 * j][0], s[2 * j][1]); w.y = cvtpk(s[2 * j][2], s[2 * j][3]); w.z = cvtpk(s[2 * j + 1][0], s[2 * j + 1][1]); w.w = cvtpk(s[2 * j + 1][2], s[2 * j + 1][3]); pf[j] = __builtin_bit_cast(ab8, w); }
; }
; template <bool PV, bool WITHL>
; DEV void pv64(const LAS unsigned char* Vb, const AttnCtx& C, const ab8 (&pf)[2][2], f32x4 (&O)[2][4], f32x4 (&L)[2], bool a0, bool a1) {
;     if (PV) {
;         const int vr = 4 * C.q4 + (C.n >> 2), vc = (C.n & 3) >> 1, vs = 8 * (C.n & 1);
;         ab8 vf[4][2];
; #pragma unroll
;         for (int dt = 0; dt < 4; ++dt)
; #pragma unroll
.LBB0_1222:
	s_cmp_ge_i32 s28, s23
	s_cbranch_scc1 .LBB0_1248
	s_waitcnt lgkmcnt(0)
	s_and_b32 s28, s100, 0xffff
	s_lshr_b32 s8, s100, 16
	s_and_b32 s9, s8, 0xff
	s_cmp_eq_u32 s9, 0
	s_cbranch_scc1 .LBB0_1248
	s_cmp_ge_i32 s28, s22
	s_cbranch_scc1 .Lmy_orig_2
	s_and_b32 s9, s8, 15
	s_and_b32 s10, s8, 0xf0
	s_cmp_lg_u32 s9, 0
	s_cselect_b32 s11, 1, 0
	s_cmp_lg_u32 s10, 0
	s_cselect_b32 s12, 1, 0
	s_add_i32 s13, s11, s12
	s_cmp_eq_u32 s13, 2
	s_cbranch_scc1 .Lmy_orig_2
	s_cmp_eq_u32 s11, 1
	s_cbranch_scc0 .Lmy_f1_2
	v_add3_u32 v228, s27, v199, v198
	v_add3_u32 v229, s27, v197, v198
	ds_read_b128 v[66:69], v228 offset:32768
	ds_read_b128 v[70:73], v229 offset:32768
	ds_read_b128 v[74:77], v228 offset:34816
	ds_read_b128 v[78:81], v229 offset:34816
	ds_read_b128 v[82:85], v228 offset:36864
	ds_read_b128 v[86:89], v229 offset:36864
	ds_read_b128 v[90:93], v228 offset:38912
	ds_read_b128 v[94:97], v229 offset:38912
	v_and_b32_e32 v239, s8, v206
	v_cmp_ne_u32_e64 s[10:11], 0, v239
	v_cmp_eq_f32_e64 s[12:13], s3, v213
	v_add_u32_e32 v234, s27, v200
	v_add3_u32 v235, v234, v201, v209
	v_add3_u32 v236, v234, v202, v209
	v_cndmask_b32_e64 v230, v213, 0, s[12:13]
	v_sub_f32_e32 v230, v175, v230
	v_add3_u32 v237, v234, v203, v209
	v_add3_u32 v238, v234, v204, v209
	v_cndmask_b32_e64 v230, v173, v230, s[10:11]
	s_and_b64 s[12:13], s[10:11], s[12:13]
	v_mov_b32_e32 v231, v230
	v_mov_b32_e32 v232, v230
	v_mov_b32_e32 v233, v230
	s_waitcnt lgkmcnt(0)
	v_mfma_f32_16x16x32_bf16 v[66:69], v[66:69], v[2:5], v[230:233]
	v_mfma_f32_16x16x32_bf16 v[74:77], v[74:77], v[2:5], v[230:233]
	v_mfma_f32_16x16x32_bf16 v[82:85], v[82:85], v[2:5], v[230:233]
	v_mfma_f32_16x16x32_bf16 v[90:93], v[90:93], v[2:5], v[230:233]
	v_mfma_f32_16x16x32_bf16 v[66:69], v[70:73], v[6:9], v[66:69]
	v_mfma_f32_16x16x32_bf16 v[74:77], v[78:81], v[6:9], v[74:77]
	v_mfma_f32_16x16x32_bf16 v[82:85], v[86:89], v[6:9], v[82:85]
	v_mfma_f32_16x16x32_bf16 v[90:93], v[94:97], v[6:9], v[90:93]
	ds_read_b64_tr_b16 v[98:99], v235 offset:40960
	ds_read_b64_tr_b16 v[100:101], v235 offset:43008
	ds_read_b64_tr_b16 v[102:103], v235 offset:45056
	ds_read_b64_tr_b16 v[104:105], v235 offset:47104
	ds_read_b64_tr_b16 v[106:107], v236 offset:40960
	ds_read_b64_tr_b16 v[108:109], v236 offset:43008
	ds_read_b64_tr_b16 v[110:111], v236 offset:45056
	ds_read_b64_tr_b16 v[112:113], v236 offset:47104
	ds_read_b64_tr_b16 v[114:115], v237 offset:40960
	ds_read_b64_tr_b16 v[116:117], v237 offset:43008
	ds_read_b64_tr_b16 v[118:119], v237 offset:45056
	ds_read_b64_tr_b16 v[120:121], v237 offset:47104
	ds_read_b64_tr_b16 v[122:123], v238 offset:40960
	ds_read_b64_tr_b16 v[124:125], v238 offset:43008
	ds_read_b64_tr_b16 v[126:127], v238 offset:45056
	ds_read_b64_tr_b16 v[128:129], v238 offset:47104
	v_max3_f32 v239, v66, v67, v68
	v_max3_f32 v240, v69, v74, v75
	v_max3_f32 v241, v76, v77, v82
	v_max3_f32 v242, v83, v84, v85
	v_max3_f32 v239, v239, v240, v90
	v_max3_f32 v241, v241, v242, v91
	v_max3_f32 v239, v239, v92, v93
	v_max_f32_e32 v239, v239, v241
	v_cmp_lt_f32_e32 vcc, s96, v239
	s_or_b64 s[12:13], s[12:13], vcc
	s_cmp_lg_u64 s[12:13], 0
	s_cbranch_scc1 .Lmy_slow_0_2
	v_exp_f32_e32 v66, v66
	v_exp_f32_e32 v67, v67
	v_exp_f32_e32 v68, v68
	v_exp_f32_e32 v69, v69
	v_exp_f32_e32 v74, v74
	v_exp_f32_e32 v75, v75
	v_exp_f32_e32 v76, v76
	v_exp_f32_e32 v77, v77
	v_exp_f32_e32 v82, v82
	v_exp_f32_e32 v83, v83
	v_exp_f32_e32 v84, v84
	v_exp_f32_e32 v85, v85
	v_exp_f32_e32 v90, v90
	v_exp_f32_e32 v91, v91
	v_exp_f32_e32 v92, v92
	v_exp_f32_e32 v93, v93
	v_cvt_pk_bf16_f32 v130, v66, v67
	v_cvt_pk_bf16_f32 v131, v68, v69
	v_cvt_pk_bf16_f32 v132, v74, v75
	v_cvt_pk_bf16_f32 v133, v76, v77
	v_cvt_pk_bf16_f32 v134, v82, v83
	v_cvt_pk_bf16_f32 v135, v84, v85
	v_cvt_pk_bf16_f32 v136, v90, v91
	v_cvt_pk_bf16_f32 v137, v92, v93
	s_nop 1
	s_waitcnt lgkmcnt(12)
	v_mfma_f32_16x16x32_bf16 v[62:65], v[98:101], v[130:133], v[62:65]
	v_mfma_f32_16x16x32_bf16 v[58:61], v[22:25], v[130:133], v[58:61]
	v_mfma_f32_16x16x32_bf16 v[62:65], v[102:105], v[134:137], v[62:65]
	s_waitcnt lgkmcnt(8)
	v_mfma_f32_16x16x32_bf16 v[54:57], v[106:109], v[130:133], v[54:57]
	v_mfma_f32_16x16x32_bf16 v[54:57], v[110:113], v[134:137], v[54:57]
	s_waitcnt lgkmcnt(4)
	v_mfma_f32_16x16x32_bf16 v[50:53], v[114:117], v[130:133], v[50:53]
	v_mfma_f32_16x16x32_bf16 v[58:61], v[22:25], v[134:137], v[58:61]
	v_mfma_f32_16x16x32_bf16 v[50:53], v[118:121], v[134:137], v[50:53]
	s_waitcnt lgkmcnt(0)
	v_mfma_f32_16x16x32_bf16 v[46:49], v[122:125], v[130:133], v[46:49]
	v_mfma_f32_16x16x32_bf16 v[46:49], v[126:129], v[134:137], v[46:49]
	s_nop 7
	s_branch .LBB0_1248

; DEV void qk64(const LAS unsigned char* Kb, const AttnCtx& C, const ab8 (&qf)[2][2], f32x4 (&s)[2][4], float init0, float init1, bool a0, bool a1) {
;     ab8 k0[4], k1[4];
; #pragma unroll
;     for (int kt = 0; kt < 4; ++kt) { k0[kt] = *(const LAS ab8*)(Kb + swz(16 * kt + C.n, C.q4)); k1[kt] = *(const LAS ab8*)(Kb + swz(16 * kt + C.n, 4 + C.q4)); }
;     __builtin_amdgcn_sched_barrier(0);
; #pragma unroll
;     for (int kt = 0; kt < 4; ++kt) {
;         if (a0) { f32x4 c = {init0, init0, init0, init0}; c = __builtin_amdgcn_mfma_f32_16x16x32_bf16(k0[kt], qf[0][0], c, 0, 0, 0); s[0][kt] = __builtin_amdgcn_mfma_f32_16x16x32_bf16(k1[kt], qf[0][1], c, 0, 0, 0); }
;         if (a1) { f32x4 c = {init1, init1, init1, init1}; c = __builtin_amdgcn_mfma_f32_16x16x32_bf16(k0[kt], qf[1][0], c, 0, 0, 0); s[1][kt] = __builtin_amdgcn_mfma_f32_16x16x32_bf16(k1[kt], qf[1][1], c, 0, 0, 0); }
; DEV void ref_step(f32x4 (&s)[4], float& m, f32x4 (&O)[4], f32x4& L, ab8 (&pf)[2], bool colact) {
;     ...
;     const bool slow = (colact && m == NEG_INF) || mx > 64.f;
;     if (__any(slow)) {
;         mx = fmaxf(mx, __shfl_xor(mx, 16)); mx = fmaxf(mx, __shfl_xor(mx, 32));
;         const bool un = (m == NEG_INF);
;         const float d = (mx == NEG_INF) ? 0.f : (un ? mx : fmaxf(mx, 0.f));
;         const float sc = un ? 1.f : __builtin_amdgcn_exp2f(-d);
; #pragma unroll
;         for (int kt = 0; kt < 4; ++kt) s[kt] = s[kt] - d;
; #pragma unroll
;         for (int dt = 0; dt < 4; ++dt) O[dt] = O[dt] * sc;
;         L = L * sc;
;         m = un ? ((mx == NEG_INF) ? NEG_INF : mx) : m + d;
;     }
; #pragma unroll
;     for (int kt = 0; kt < 4; ++kt)
; #pragma unroll
;         for (int i = 0; i < 4; ++i) s[kt][i] = __builtin_amdgcn_exp2f(s[kt][i]);
; #pragma unroll
;     for (int j = 0; j < 2; ++j) { v4u w; w.x = cvtpk(s[2 * j][0], s[2 * j][1]); w.y = cvtpk(s[2 * j][2], s[2 * j][3]); w.z = cvtpk(s[2 * j + 1][0], s[2 * j + 1][1]); w.w = cvtpk(s[2 * j + 1][2], s[2 * j + 1][3]); pf[j] = __builtin_bit_cast(ab8, w); }
; }
; template <bool PV, bool WITHL>
; DEV void pv64(const LAS unsigned char* Vb, const AttnCtx& C, const ab8 (&pf)[2][2], f32x4 (&O)[2][4], f32x4 (&L)[2], bool a0, bool a1) {
;     if (PV) {
;         const int vr = 4 * C.q4 + (C.n >> 2), vc = (C.n & 3) >> 1, vs = 8 * (C.n & 1);
;         ab8 vf[4][2];
; #pragma unroll
;         for (int dt = 0; dt < 4; ++dt)
; #pragma unroll
.Lmy_f1_2:
	v_add3_u32 v228, s27, v199, v198
	v_add3_u32 v229, s27, v197, v198
	ds_read_b128 v[66:69], v228 offset:32768
	ds_read_b128 v[70:73], v229 offset:32768
	ds_read_b128 v[74:77], v228 offset:34816
	ds_read_b128 v[78:81], v229 offset:34816
	ds_read_b128 v[82:85], v228 offset:36864
	ds_read_b128 v[86:89], v229 offset:36864
	ds_read_b128 v[90:93], v228 offset:38912
	ds_read_b128 v[94:97], v229 offset:38912
	v_and_b32_e32 v239, s8, v207
	v_cmp_ne_u32_e64 s[10:11], 0, v239
	v_cmp_eq_f32_e64 s[12:13], s3, v212
	v_add_u32_e32 v234, s27, v200
	v_add3_u32 v235, v234, v201, v209
	v_add3_u32 v236, v234, v202, v209
	v_cndmask_b32_e64 v230, v212, 0, s[12:13]
	v_sub_f32_e32 v230, v175, v230
	v_add3_u32 v237, v234, v203, v209
	v_add3_u32 v238, v234, v204, v209
	v_cndmask_b32_e64 v230, v173, v230, s[10:11]
	s_and_b64 s[12:13], s[10:11], s[12:13]
	v_mov_b32_e32 v231, v230
	v_mov_b32_e32 v232, v230
	v_mov_b32_e32 v233, v230
	s_waitcnt lgkmcnt(0)
	v_mfma_f32_16x16x32_bf16 v[66:69], v[66:69], v[10:13], v[230:233]
	v_mfma_f32_16x16x32_bf16 v[74:77], v[74:77], v[10:13], v[230:233]
	v_mfma_f32_16x16x32_bf16 v[82:85], v[82:85], v[10:13], v[230:233]
	v_mfma_f32_16x16x32_bf16 v[90:93], v[90:93], v[10:13], v[230:233]
	v_mfma_f32_16x16x32_bf16 v[66:69], v[70:73], v[14:17], v[66:69]
	v_mfma_f32_16x16x32_bf16 v[74:77], v[78:81], v[14:17], v[74:77]
	v_mfma_f32_16x16x32_bf16 v[82:85], v[86:89], v[14:17], v[82:85]
	v_mfma_f32_16x16x32_bf16 v[90:93], v[94:97], v[14:17], v[90:93]
	ds_read_b64_tr_b16 v[98:99], v235 offset:40960
	ds_read_b64_tr_b16 v[100:101], v235 offset:43008
	ds_read_b64_tr_b16 v[102:103], v235 offset:45056
	ds_read_b64_tr_b16 v[104:105], v235 offset:47104
	ds_read_b64_tr_b16 v[106:107], v236 offset:40960
	ds_read_b64_tr_b16 v[108:109], v236 offset:43008
	ds_read_b64_tr_b16 v[110:111], v236 offset:45056
	ds_read_b64_tr_b16 v[112:113], v236 offset:47104
	ds_read_b64_tr_b16 v[114:115], v237 offset:40960
	ds_read_b64_tr_b16 v[116:117], v237 offset:43008
	ds_read_b64_tr_b16 v[118:119], v237 offset:45056
	ds_read_b64_tr_b16 v[120:121], v237 offset:47104
	ds_read_b64_tr_b16 v[122:123], v238 offset:40960
	ds_read_b64_tr_b16 v[124:125], v238 offset:43008
	ds_read_b64_tr_b16 v[126:127], v238 offset:45056
	ds_read_b64_tr_b16 v[128:129], v238 offset:47104
	v_max3_f32 v239, v66, v67, v68
	v_max3_f32 v240, v69, v74, v75
	v_max3_f32 v241, v76, v77, v82
	v_max3_f32 v242, v83, v84, v85
	v_max3_f32 v239, v239, v240, v90
	v_max3_f32 v241, v241, v242, v91
	v_max3_f32 v239, v239, v92, v93
	v_max_f32_e32 v239, v239, v241
	v_cmp_lt_f32_e32 vcc, s96, v239
	s_or_b64 s[12:13], s[12:13], vcc
	s_cmp_lg_u64 s[12:13], 0
	s_cbranch_scc1 .Lmy_slow_1_2
	v_exp_f32_e32 v66, v66
	v_exp_f32_e32 v67, v67
	v_exp_f32_e32 v68, v68
	v_exp_f32_e32 v69, v69
	v_exp_f32_e32 v74, v74
	v_exp_f32_e32 v75, v75
	v_exp_f32_e32 v76, v76
	v_exp_f32_e32 v77, v77
	v_exp_f32_e32 v82, v82
	v_exp_f32_e32 v83, v83
	v_exp_f32_e32 v84, v84
	v_exp_f32_e32 v85, v85
	v_exp_f32_e32 v90, v90
	v_exp_f32_e32 v91, v91
	v_exp_f32_e32 v92, v92
	v_exp_f32_e32 v93, v93
	v_cvt_pk_bf16_f32 v130, v66, v67
	v_cvt_pk_bf16_f32 v131, v68, v69
	v_cvt_pk_bf16_f32 v132, v74, v75
	v_cvt_pk_bf16_f32 v133, v76, v77
	v_cvt_pk_bf16_f32 v134, v82, v83
	v_cvt_pk_bf16_f32 v135, v84, v85
	v_cvt_pk_bf16_f32 v136, v90, v91
	v_cvt_pk_bf16_f32 v137, v92, v93
	s_nop 1
	s_waitcnt lgkmcnt(12)
	v_mfma_f32_16x16x32_bf16 v[38:41], v[98:101], v[130:133], v[38:41]
	v_mfma_f32_16x16x32_bf16 v[42:45], v[22:25], v[130:133], v[42:45]
	v_mfma_f32_16x16x32_bf16 v[38:41], v[102:105], v[134:137], v[38:41]
	s_waitcnt lgkmcnt(8)
	v_mfma_f32_16x16x32_bf16 v[34:37], v[106:109], v[130:133], v[34:37]
	v_mfma_f32_16x16x32_bf16 v[34:37], v[110:113], v[134:137], v[34:37]
	s_waitcnt lgkmcnt(4)
	v_mfma_f32_16x16x32_bf16 v[30:33], v[114:117], v[130:133], v[30:33]
	v_mfma_f32_16x16x32_bf16 v[42:45], v[22:25], v[134:137], v[42:45]
	v_mfma_f32_16x16x32_bf16 v[30:33], v[118:121], v[134:137], v[30:33]
	s_waitcnt lgkmcnt(0)
	v_mfma_f32_16x16x32_bf16 v[26:29], v[122:125], v[130:133], v[26:29]
	v_mfma_f32_16x16x32_bf16 v[26:29], v[126:129], v[134:137], v[26:29]
	s_nop 7
	s_branch .LBB0_1248

; #define NEG_INF (-__builtin_inff())
; template <bool LUTB, bool WINLO>
; DEV void mask_bias(f32x4 (&s)[4], const AttnCtx& C, int t, int p0, int pstep, bool colok) {
; #pragma unroll
;     for (int kt = 0; kt < 4; ++kt)
; #pragma unroll
;         for (int i = 0; i < 4; ++i) { const int rel = t - (p0 + pstep * (16 * kt + 4 * C.q4 + i));
;             bool ok = colok && rel >= 0; if (WINLO) ok = ok && rel < 512;
;             float v = s[kt][i]; if (LUTB) v += C.lut[C.h * 129 + (rel < 0 ? 0 : (rel < 128 ? rel : 128))];
;             s[kt][i] = ok ? v : NEG_INF; }
; }
; DEV void attn_unit_mfma(Frame& F, int qg, int kv) {
;     ...
;         const int j = lst[1 + i]; const unsigned byte = (msk[2 * j + (w >> 2)] >> (8 * (w & 3))) & 0xffu;
;         const bool a0 = (byte & 0xfu) != 0u, a1 = (byte & 0xf0u) != 0u;
;         if (a0 || a1) {
;             const bool near = j >= cur - 2; const float bi = near ? 0.f : C.b31;
;             const bool c0 = ((byte >> (C.n >> 2)) & 1u) != 0u, c1 = ((byte >> (4 + (C.n >> 2))) & 1u) != 0u;
;     ...
;             if (a0 && a1) SEL_BODY(true, true); else if (a0) SEL_BODY(true, false); else SEL_BODY(false, true);
.Lmy_orig_2:
	s_and_b32 s9, s8, 15
	s_cmp_eq_u32 s9, 0
	s_cselect_b64 s[14:15], -1, 0
	s_cmp_lg_u32 s9, 0
	s_cselect_b64 s[12:13], -1, 0
	s_and_b32 s9, s8, 0xf0
	s_cmp_lg_u32 s9, 0
	s_cselect_b64 s[16:17], -1, 0
	s_cmp_ge_i32 s28, s22
	s_cselect_b64 s[18:19], -1, 0
	s_cmp_lt_i32 s28, s22
	v_and_b32_e32 v66, s8, v206
	s_cselect_b64 vcc, -1, 0
	v_cmp_ne_u32_e64 s[10:11], 0, v66
	v_and_b32_e32 v66, s8, v207
	s_and_b64 s[16:17], s[12:13], s[16:17]
	v_cndmask_b32_e32 v216, 0, v175, vcc
	v_cmp_ne_u32_e64 s[8:9], 0, v66
	s_mov_b64 s[12:13], -1
	s_and_b64 vcc, exec, s[16:17]
	v_add3_u32 v215, s27, v199, v198
	v_add3_u32 v214, s27, v197, v198
	s_cbranch_vccnz .LBB0_1238
	ds_read_b128 v[70:73], v215 offset:32768
	ds_read_b128 v[74:77], v215 offset:34816
	ds_read_b128 v[90:93], v214 offset:32768
	ds_read_b128 v[78:81], v214 offset:34816
	ds_read_b128 v[82:85], v215 offset:36864
	ds_read_b128 v[86:89], v215 offset:38912
	ds_read_b128 v[94:97], v214 offset:36864
	ds_read_b128 v[66:69], v214 offset:38912
	s_andn2_b64 vcc, exec, s[14:15]
	s_cbranch_vccnz .LBB0_1231
	v_cmp_eq_f32_e64 s[12:13], s3, v212
	s_nop 1
	v_cndmask_b32_e64 v98, v212, 0, s[12:13]
	v_sub_f32_e32 v98, v216, v98
	v_cndmask_b32_e64 v102, v173, v98, s[8:9]
	v_mov_b32_e32 v103, v102
	v_mov_b32_e32 v104, v102
	v_mov_b32_e32 v105, v102
	s_andn2_b64 vcc, exec, s[18:19]
	s_waitcnt lgkmcnt(0)
	v_mfma_f32_16x16x32_bf16 v[98:101], v[70:73], v[10:13], v[102:105]
	v_mfma_f32_16x16x32_bf16 v[110:113], v[90:93], v[14:17], v[98:101]
	v_mfma_f32_16x16x32_bf16 v[98:101], v[74:77], v[10:13], v[102:105]
	v_mfma_f32_16x16x32_bf16 v[106:109], v[78:81], v[14:17], v[98:101]
	v_mfma_f32_16x16x32_bf16 v[98:101], v[82:85], v[10:13], v[102:105]
	v_mfma_f32_16x16x32_bf16 v[102:105], v[86:89], v[10:13], v[102:105]
	v_mfma_f32_16x16x32_bf16 v[98:101], v[94:97], v[14:17], v[98:101]
	v_mfma_f32_16x16x32_bf16 v[102:105], v[66:69], v[14:17], v[102:105]
	s_cbranch_vccnz .LBB0_1228
	s_lshl_b32 s14, s28, 6
	v_subrev_u32_e32 v122, s14, v144
	v_sub_u32_e32 v123, v122, v20
	v_add_u32_e32 v124, v122, v208
	v_add_u32_e32 v125, -3, v123
	v_add_u32_e32 v126, -2, v123
	v_subrev_u32_e32 v127, 17, v123
	v_add_u32_e32 v128, -16, v123
	v_subrev_u32_e32 v129, 33, v123
	v_subrev_u32_e32 v130, 32, v123
	v_med3_i32 v114, v123, 0, v172
	v_med3_i32 v115, v124, 0, v172
	v_med3_i32 v116, v126, 0, v172
	v_med3_i32 v117, v125, 0, v172
	v_med3_i32 v118, v128, 0, v172
	v_med3_i32 v119, v127, 0, v172
	v_med3_i32 v120, v130, 0, v172
	v_med3_i32 v121, v129, 0, v172
	v_lshl_add_u32 v114, v114, 2, v174
	v_lshl_add_u32 v115, v115, 2, v174
	v_lshl_add_u32 v116, v116, 2, v174
	v_lshl_add_u32 v117, v117, 2, v174
	v_lshl_add_u32 v118, v118, 2, v174
	v_lshl_add_u32 v119, v119, 2, v174
	v_lshl_add_u32 v120, v120, 2, v174
	v_lshl_add_u32 v121, v121, 2, v174
	ds_read_b32 v114, v114
	ds_read_b32 v115, v115
	ds_read_b32 v116, v116
	ds_read_b32 v117, v117
	ds_read_b32 v118, v118
	ds_read_b32 v119, v119
	ds_read_b32 v120, v120
	ds_read_b32 v121, v121
	s_waitcnt lgkmcnt(0)
	v_pk_add_f32 v[110:111], v[110:111], v[114:115]
	v_cmp_lt_i32_e32 vcc, -1, v124
	v_pk_add_f32 v[112:113], v[112:113], v[116:117]
	v_sub_u32_e32 v116, v122, v158
	v_cndmask_b32_e32 v111, v173, v111, vcc
	v_cmp_lt_i32_e32 vcc, -1, v123
	v_sub_u32_e32 v117, v122, v1
	v_subrev_u32_e32 v124, 49, v123
	v_cndmask_b32_e32 v110, v173, v110, vcc
	v_cmp_lt_i32_e32 vcc, -1, v125
	v_subrev_u32_e32 v125, 48, v123
	v_add_u32_e32 v131, -16, v116
	v_cndmask_b32_e32 v113, v173, v113, vcc
	v_cmp_lt_i32_e32 vcc, -1, v126
	v_add_u32_e32 v126, -16, v117
	v_subrev_u32_e32 v132, 32, v117
	v_subrev_u32_e32 v133, 32, v116
	v_subrev_u32_e32 v135, 48, v116
	v_med3_i32 v114, v125, 0, v172
	v_med3_i32 v115, v124, 0, v172
	v_med3_i32 v122, v131, 0, v172
	v_med3_i32 v123, v126, 0, v172
	v_pk_add_f32 v[106:107], v[106:107], v[118:119]
	v_med3_i32 v118, v133, 0, v172
	v_med3_i32 v119, v132, 0, v172
	v_subrev_u32_e32 v134, 48, v117
	v_med3_i32 v116, v135, 0, v172
	v_lshl_add_u32 v114, v114, 2, v174
	v_lshl_add_u32 v115, v115, 2, v174
	v_lshl_add_u32 v122, v122, 2, v174
	v_lshl_add_u32 v123, v123, 2, v174
	v_lshl_add_u32 v118, v118, 2, v174
	v_lshl_add_u32 v119, v119, 2, v174
	v_lshl_add_u32 v136, v116, 2, v174
	v_med3_i32 v116, v134, 0, v172
	v_lshl_add_u32 v137, v116, 2, v174
	ds_read_b32 v114, v114
	ds_read_b32 v115, v115
	ds_read_b32 v116, v122
	ds_read_b32 v117, v123
	ds_read_b32 v118, v118
	ds_read_b32 v119, v119
	ds_read_b32 v122, v136
	ds_read_b32 v123, v137
	v_cndmask_b32_e32 v112, v173, v112, vcc
	s_waitcnt lgkmcnt(0)
	v_pk_add_f32 v[108:109], v[108:109], v[116:117]
	v_cmp_lt_i32_e32 vcc, -1, v126
	v_pk_add_f32 v[100:101], v[100:101], v[118:119]
	v_pk_add_f32 v[98:99], v[98:99], v[120:121]
	v_cndmask_b32_e32 v109, v173, v109, vcc
	v_cmp_lt_i32_e32 vcc, -1, v131
	v_pk_add_f32 v[104:105], v[104:105], v[122:123]
	v_pk_add_f32 v[102:103], v[102:103], v[114:115]
	v_cndmask_b32_e32 v108, v173, v108, vcc
	v_cmp_lt_i32_e32 vcc, -1, v127
	s_nop 1
	v_cndmask_b32_e32 v107, v173, v107, vcc
	v_cmp_lt_i32_e32 vcc, -1, v128
	s_nop 1
	v_cndmask_b32_e32 v106, v173, v106, vcc
	v_cmp_lt_i32_e32 vcc, -1, v132
	s_nop 1
	v_cndmask_b32_e32 v101, v173, v101, vcc
	v_cmp_lt_i32_e32 vcc, -1, v133
	s_nop 1
	v_cndmask_b32_e32 v100, v173, v100, vcc
	v_cmp_lt_i32_e32 vcc, -1, v129
	s_nop 1
	v_cndmask_b32_e32 v99, v173, v99, vcc
	v_cmp_lt_i32_e32 vcc, -1, v130
	s_nop 1
	v_cndmask_b32_e32 v98, v173, v98, vcc
	v_cmp_lt_i32_e32 vcc, -1, v134
	s_nop 1
	v_cndmask_b32_e32 v105, v173, v105, vcc
	v_cmp_lt_i32_e32 vcc, -1, v135
	s_nop 1
	v_cndmask_b32_e32 v104, v173, v104, vcc
	v_cmp_lt_i32_e32 vcc, -1, v124
	s_nop 1
	v_cndmask_b32_e32 v103, v173, v103, vcc
	v_cmp_lt_i32_e32 vcc, -1, v125
	s_nop 1
	v_cndmask_b32_e32 v102, v173, v102, vcc
